# fox: fast path for diagonal tiles (causal mask via cmp/cndmask), fallback to original body
# speedup vs baseline: 1.0134x; 1.0044x over previous
; DI float ex2(float x) { return __builtin_amdgcn_exp2f(x); }
; DI f32x4 mmaT(bf16x8 a_m, bf16x8 b_n, f32x4 c) { return __builtin_amdgcn_mfma_f32_16x16x32_bf16(b_n, a_m, c, 0, 0, 0); }
; template <bool DIAG>
; DI void fox_tile(const bf16_t* sK, const bf16_t* sV, const float* sFk, const bf16x8 (&qf)[2][2], f32x4 (&o)[2][4], float (&mrun)[2], float (&lsum)[2], int key0, int qg0, int fr, int fq, int lane) {
;   const float SC2 = 0.125f * LOG2E;
;   f32x4 s[2][4];
;   const int kof = (fr * 64 + fq * 16) ^ ((fr >> 3) << 5);
; #pragma unroll
;   for (int t = 0; t < 4; ++t) {
;     const bf16x8 k0 = *(const bf16x8*)((const unsigned char*)sK + (t * 2) * 1024 + kof), k1 = *(const bf16x8*)((const unsigned char*)sK + (t * 2 + 1) * 1024 + kof);
; #pragma unroll
;     for (int mi = 0; mi < 2; ++mi) { s[mi][t] = mmaT(qf[mi][0], k0, (f32x4){0.f, 0.f, 0.f, 0.f}); s[mi][t] = mmaT(qf[mi][1], k1, s[mi][t]); }
;   }
;   f32x4 fk[4];
; #pragma unroll
;   for (int t = 0; t < 4; ++t) fk[t] = *(const f32x4*)(sFk + 16 * t + 4 * fq);
;   __builtin_amdgcn_sched_barrier(0);
;   bf16x8 vf[2][4];
; #pragma unroll
;   for (int k2 = 0; k2 < 2; ++k2)
; #pragma unroll
;     for (int d = 0; d < 4; ++d) {
;       const bf16_t* a = sV + (32 * k2 + 4 * fq + (fr >> 2)) * 72 + 16 * d + 4 * (fr & 3);
;       const v4i16_t lo = tr_rd(a), hi = tr_rd(a + 16 * 72);
;       vf[k2][d] = __builtin_shufflevector(lo, hi, 0, 1, 2, 3, 4, 5, 6, 7);
;     }
;   __builtin_amdgcn_sched_barrier(0);
; #pragma unroll
;   for (int mi = 0; mi < 2; ++mi) {
;     float mx = -INFINITY;
; #pragma unroll
;     for (int t = 0; t < 4; ++t)
; #pragma unroll
;       for (int j = 0; j < 4; ++j) {
;         float x = __builtin_fmaf(s[mi][t][j], SC2, fk[t][j]);
;         if (DIAG) { if (key0 + 16 * t + 4 * fq + j > qg0 + 16 * mi) x = -INFINITY; }
;         s[mi][t][j] = x; mx = fmaxf(mx, x);
;       }
;     mx = fmaxf(mx, shx(mx, 16, lane)); mx = fmaxf(mx, shx(mx, 32, lane));
;     const float mnew = fmaxf(mrun[mi], mx), alpha = ex2(mrun[mi] - mnew);
;     mrun[mi] = mnew;
;     float ps = 0.f;
; #pragma unroll
;     for (int t = 0; t < 4; ++t)
; #pragma unroll
;       for (int j = 0; j < 4; ++j) { const float pv = ex2(s[mi][t][j] - mnew); s[mi][t][j] = pv; ps += pv; }
;     lsum[mi] = lsum[mi] * alpha + ps;
; #pragma unroll
;     for (int d = 0; d < 4; ++d) o[mi][d] *= alpha;
;   }
.LBB0_489:
	s_mul_i32 s4, s21, 0x4900
	s_add_i32 s4, s4, 32
	v_add_u32_e32 v24, s4, v213
	ds_read_b128 v[64:67], v24
	ds_read_b128 v[68:71], v24 offset:1024
	ds_read_b128 v[56:59], v24 offset:2048
	ds_read_b128 v[60:63], v24 offset:3072
	ds_read_b128 v[48:51], v24 offset:4096
	ds_read_b128 v[52:55], v24 offset:5120
	ds_read_b128 v[40:43], v24 offset:6144
	ds_read_b128 v[44:47], v24 offset:7168
	v_lshl_add_u32 v24, v209, 2, s4
	ds_read_b128 v[36:39], v24 offset:18432
	ds_read_b128 v[32:35], v24 offset:18496
	ds_read_b128 v[28:31], v24 offset:18560
	ds_read_b128 v[24:27], v24 offset:18624
	v_lshl_add_u32 v72, v214, 1, s4
	v_readfirstlane_b32 s100, v212
	s_add_i32 s101, s18, 94
	s_mov_b64 s[4:5], -1
	v_add_u32_e32 v221, v72, v215
	s_cmp_le_i32 s101, s100
	s_cbranch_scc1 .LBB0_491
	s_waitcnt lgkmcnt(11)
	v_mfma_f32_16x16x32_bf16 v[72:75], v[64:67], v[0:3], v[224:227]
	s_waitcnt lgkmcnt(10)
	v_mfma_f32_16x16x32_bf16 v[72:75], v[68:71], v[4:7], v[72:75]
	s_waitcnt lgkmcnt(9)
	v_mfma_f32_16x16x32_bf16 v[76:79], v[56:59], v[0:3], v[224:227]
	s_waitcnt lgkmcnt(8)
	v_mfma_f32_16x16x32_bf16 v[76:79], v[60:63], v[4:7], v[76:79]
	s_waitcnt lgkmcnt(7)
	v_mfma_f32_16x16x32_bf16 v[80:83], v[48:51], v[0:3], v[224:227]
	s_waitcnt lgkmcnt(6)
	v_mfma_f32_16x16x32_bf16 v[80:83], v[52:55], v[4:7], v[80:83]
	s_waitcnt lgkmcnt(5)
	v_mfma_f32_16x16x32_bf16 v[96:99], v[40:43], v[0:3], v[224:227]
	s_waitcnt lgkmcnt(4)
	v_mfma_f32_16x16x32_bf16 v[96:99], v[44:47], v[4:7], v[96:99]
	s_waitcnt lgkmcnt(0)
	v_add_u32_e32 v172, s18, v209
	v_sub_u32_e32 v172, v172, v206
	v_add_u32_e32 v176, -16, v172
	v_add_u32_e32 v173, 16, v172
	v_add_u32_e32 v177, 16, v176
	v_add_u32_e32 v174, 32, v172
	v_add_u32_e32 v178, 32, v176
	v_add_u32_e32 v175, 48, v172
	v_add_u32_e32 v179, 48, v176
	v_mfma_f32_16x16x32_bf16 v[84:87], v[64:67], v[8:11], v[228:231]
	v_mfma_f32_16x16x32_bf16 v[84:87], v[68:71], v[12:15], v[84:87]
	v_fmamk_f32 v72, v72, 0x3e38aa3b, v36
	v_fmamk_f32 v73, v73, 0x3e38aa3b, v37
	v_fmamk_f32 v74, v74, 0x3e38aa3b, v38
	v_fmamk_f32 v75, v75, 0x3e38aa3b, v39
	v_mfma_f32_16x16x32_bf16 v[88:91], v[56:59], v[8:11], v[228:231]
	v_mfma_f32_16x16x32_bf16 v[88:91], v[60:63], v[12:15], v[88:91]
	v_fmamk_f32 v76, v76, 0x3e38aa3b, v32
	v_fmamk_f32 v77, v77, 0x3e38aa3b, v33
	v_fmamk_f32 v78, v78, 0x3e38aa3b, v34
	v_fmamk_f32 v79, v79, 0x3e38aa3b, v35
	v_mfma_f32_16x16x32_bf16 v[92:95], v[48:51], v[8:11], v[228:231]
	v_mfma_f32_16x16x32_bf16 v[92:95], v[52:55], v[12:15], v[92:95]
	v_fmamk_f32 v80, v80, 0x3e38aa3b, v28
	v_fmamk_f32 v81, v81, 0x3e38aa3b, v29
	v_fmamk_f32 v82, v82, 0x3e38aa3b, v30
	v_fmamk_f32 v83, v83, 0x3e38aa3b, v31
	v_mfma_f32_16x16x32_bf16 v[164:167], v[40:43], v[8:11], v[228:231]
	v_mfma_f32_16x16x32_bf16 v[164:167], v[44:47], v[12:15], v[164:167]
	v_fmamk_f32 v96, v96, 0x3e38aa3b, v24
	v_fmamk_f32 v97, v97, 0x3e38aa3b, v25
	v_fmamk_f32 v98, v98, 0x3e38aa3b, v26
	v_fmamk_f32 v99, v99, 0x3e38aa3b, v27
	ds_read_b64_tr_b16 v[68:69], v221 offset:9216
	ds_read_b64_tr_b16 v[60:61], v221 offset:9248
	ds_read_b64_tr_b16 v[64:65], v221 offset:9280
	ds_read_b64_tr_b16 v[56:57], v221 offset:9312
	ds_read_b64_tr_b16 v[70:71], v221 offset:11520
	ds_read_b64_tr_b16 v[62:63], v221 offset:11552
	ds_read_b64_tr_b16 v[66:67], v221 offset:11584
	ds_read_b64_tr_b16 v[58:59], v221 offset:11616
	ds_read_b64_tr_b16 v[52:53], v221 offset:13824
	ds_read_b64_tr_b16 v[48:49], v221 offset:13856
	ds_read_b64_tr_b16 v[44:45], v221 offset:13888
	ds_read_b64_tr_b16 v[40:41], v221 offset:13920
	ds_read_b64_tr_b16 v[54:55], v221 offset:16128
	ds_read_b64_tr_b16 v[50:51], v221 offset:16160
	ds_read_b64_tr_b16 v[46:47], v221 offset:16192
	ds_read_b64_tr_b16 v[42:43], v221 offset:16224
	v_cmp_ge_i32_e32 vcc, 0, v172
	v_cmp_ge_i32_e64 s[4:5], -1, v172
	v_cmp_ge_i32_e64 s[100:101], -2, v172
	v_cndmask_b32_e32 v72, v200, v72, vcc
	v_cndmask_b32_e64 v73, v200, v73, s[4:5]
	v_cndmask_b32_e64 v74, v200, v74, s[100:101]
	v_cmp_ge_i32_e32 vcc, -3, v172
	v_cmp_ge_i32_e64 s[4:5], 0, v173
	v_cmp_ge_i32_e64 s[100:101], -1, v173
	v_cndmask_b32_e32 v75, v200, v75, vcc
	v_cndmask_b32_e64 v76, v200, v76, s[4:5]
	v_cndmask_b32_e64 v77, v200, v77, s[100:101]
	v_cmp_ge_i32_e32 vcc, -2, v173
	v_cmp_ge_i32_e64 s[4:5], -3, v173
	v_cmp_ge_i32_e64 s[100:101], 0, v174
	v_cndmask_b32_e32 v78, v200, v78, vcc
	v_cndmask_b32_e64 v79, v200, v79, s[4:5]
	v_cndmask_b32_e64 v80, v200, v80, s[100:101]
	v_cmp_ge_i32_e32 vcc, -1, v174
	v_cmp_ge_i32_e64 s[4:5], -2, v174
	v_cmp_ge_i32_e64 s[100:101], -3, v174
; DI unsigned pk2(float lo, float hi) { unsigned r; asm volatile("v_cvt_pk_bf16_f32 %0, %1, %2" : "=v"(r) : "v"(lo), "v"(hi)); return r; }
; DI float ex2(float x) { return __builtin_amdgcn_exp2f(x); }
; DI float shx(float v, int m, int lane) { return __int_as_float(__builtin_amdgcn_ds_bpermute((lane ^ m) << 2, __float_as_int(v))); }
; template <bool DIAG>
; DI void fox_tile(const bf16_t* sK, const bf16_t* sV, const float* sFk, const bf16x8 (&qf)[2][2], f32x4 (&o)[2][4], float (&mrun)[2], float (&lsum)[2], int key0, int qg0, int fr, int fq, int lane) {
;     ...
;   for (int mi = 0; mi < 2; ++mi) {
;     float mx = -INFINITY;
; #pragma unroll
;     for (int t = 0; t < 4; ++t)
; #pragma unroll
;       for (int j = 0; j < 4; ++j) {
;         float x = __builtin_fmaf(s[mi][t][j], SC2, fk[t][j]);
;         if (DIAG) { if (key0 + 16 * t + 4 * fq + j > qg0 + 16 * mi) x = -INFINITY; }
;         s[mi][t][j] = x; mx = fmaxf(mx, x);
;       }
;     mx = fmaxf(mx, shx(mx, 16, lane)); mx = fmaxf(mx, shx(mx, 32, lane));
;     const float mnew = fmaxf(mrun[mi], mx), alpha = ex2(mrun[mi] - mnew);
;     mrun[mi] = mnew;
;     float ps = 0.f;
; #pragma unroll
;     for (int t = 0; t < 4; ++t)
; #pragma unroll
;       for (int j = 0; j < 4; ++j) { const float pv = ex2(s[mi][t][j] - mnew); s[mi][t][j] = pv; ps += pv; }
;     lsum[mi] = lsum[mi] * alpha + ps;
; #pragma unroll
;     for (int d = 0; d < 4; ++d) o[mi][d] *= alpha;
;   }
; #pragma unroll
;   for (int k2 = 0; k2 < 2; ++k2) {
;     bf16x8 pa[2];
; #pragma unroll
;     for (int mi = 0; mi < 2; ++mi) pa[mi] = mk8(pk2(s[mi][2 * k2][0], s[mi][2 * k2][1]), pk2(s[mi][2 * k2][2], s[mi][2 * k2][3]), pk2(s[mi][2 * k2 + 1][0], s[mi][2 * k2 + 1][1]), pk2(s[mi][2 * k2 + 1][2], s[mi][2 * k2 + 1][3]));
	v_cndmask_b32_e32 v81, v200, v81, vcc
	v_cndmask_b32_e64 v82, v200, v82, s[4:5]
	v_cndmask_b32_e64 v83, v200, v83, s[100:101]
	v_cmp_ge_i32_e32 vcc, 0, v175
	v_cmp_ge_i32_e64 s[4:5], -1, v175
	v_cmp_ge_i32_e64 s[100:101], -2, v175
	v_cndmask_b32_e32 v96, v200, v96, vcc
	v_cndmask_b32_e64 v97, v200, v97, s[4:5]
	v_cndmask_b32_e64 v98, v200, v98, s[100:101]
	v_cmp_ge_i32_e32 vcc, -3, v175
	s_nop 1
	v_cndmask_b32_e32 v99, v200, v99, vcc
	v_exp_f32_e32 v72, v72
	v_exp_f32_e32 v73, v73
	v_exp_f32_e32 v74, v74
	v_exp_f32_e32 v75, v75
	v_exp_f32_e32 v76, v76
	v_exp_f32_e32 v77, v77
	v_exp_f32_e32 v78, v78
	v_exp_f32_e32 v79, v79
	v_exp_f32_e32 v80, v80
	v_exp_f32_e32 v81, v81
	v_exp_f32_e32 v82, v82
	v_exp_f32_e32 v83, v83
	v_exp_f32_e32 v96, v96
	v_exp_f32_e32 v97, v97
	v_exp_f32_e32 v98, v98
	v_exp_f32_e32 v99, v99
	v_fmamk_f32 v84, v84, 0x3e38aa3b, v36
	v_fmamk_f32 v85, v85, 0x3e38aa3b, v37
	v_fmamk_f32 v86, v86, 0x3e38aa3b, v38
	v_fmamk_f32 v87, v87, 0x3e38aa3b, v39
	v_fmamk_f32 v88, v88, 0x3e38aa3b, v32
	v_fmamk_f32 v89, v89, 0x3e38aa3b, v33
	v_fmamk_f32 v90, v90, 0x3e38aa3b, v34
	v_fmamk_f32 v91, v91, 0x3e38aa3b, v35
	v_fmamk_f32 v92, v92, 0x3e38aa3b, v28
	v_fmamk_f32 v93, v93, 0x3e38aa3b, v29
	v_fmamk_f32 v94, v94, 0x3e38aa3b, v30
	v_fmamk_f32 v95, v95, 0x3e38aa3b, v31
	v_fmamk_f32 v164, v164, 0x3e38aa3b, v24
	v_fmamk_f32 v165, v165, 0x3e38aa3b, v25
	v_fmamk_f32 v166, v166, 0x3e38aa3b, v26
	v_fmamk_f32 v167, v167, 0x3e38aa3b, v27
	v_cmp_ge_i32_e32 vcc, 0, v176
	v_cmp_ge_i32_e64 s[4:5], -1, v176
	v_cmp_ge_i32_e64 s[100:101], -2, v176
	v_cndmask_b32_e32 v84, v200, v84, vcc
	v_cndmask_b32_e64 v85, v200, v85, s[4:5]
	v_cndmask_b32_e64 v86, v200, v86, s[100:101]
	v_cmp_ge_i32_e32 vcc, -3, v176
	v_cmp_ge_i32_e64 s[4:5], 0, v177
	v_cmp_ge_i32_e64 s[100:101], -1, v177
	v_cndmask_b32_e32 v87, v200, v87, vcc
	v_cndmask_b32_e64 v88, v200, v88, s[4:5]
	v_cndmask_b32_e64 v89, v200, v89, s[100:101]
	v_cmp_ge_i32_e32 vcc, -2, v177
	v_cmp_ge_i32_e64 s[4:5], -3, v177
	v_cmp_ge_i32_e64 s[100:101], 0, v178
	v_cndmask_b32_e32 v90, v200, v90, vcc
	v_cndmask_b32_e64 v91, v200, v91, s[4:5]
	v_cndmask_b32_e64 v92, v200, v92, s[100:101]
	v_cmp_ge_i32_e32 vcc, -1, v178
	v_cmp_ge_i32_e64 s[4:5], -2, v178
	v_cmp_ge_i32_e64 s[100:101], -3, v178
	v_cndmask_b32_e32 v93, v200, v93, vcc
	v_cndmask_b32_e64 v94, v200, v94, s[4:5]
	v_cndmask_b32_e64 v95, v200, v95, s[100:101]
	v_cmp_ge_i32_e32 vcc, 0, v179
	v_cmp_ge_i32_e64 s[4:5], -1, v179
	v_cmp_ge_i32_e64 s[100:101], -2, v179
	v_cndmask_b32_e32 v164, v200, v164, vcc
	v_cndmask_b32_e64 v165, v200, v165, s[4:5]
	v_cndmask_b32_e64 v166, v200, v166, s[100:101]
	v_cmp_ge_i32_e32 vcc, -3, v179
	s_nop 1
	v_cndmask_b32_e32 v167, v200, v167, vcc
	v_add_f32_e32 v146, v72, v73
	v_add_f32_e32 v147, v74, v75
	v_add_f32_e32 v148, v76, v77
	v_add_f32_e32 v149, v78, v79
	v_add_f32_e32 v150, v80, v81
	v_add_f32_e32 v151, v82, v83
	v_add_f32_e32 v152, v96, v97
	v_add_f32_e32 v153, v98, v99
	v_add_f32_e32 v146, v146, v147
	v_add_f32_e32 v147, v148, v149
	v_add_f32_e32 v148, v150, v151
	v_add_f32_e32 v149, v152, v153
	v_add_f32_e32 v146, v146, v147
	v_add_f32_e32 v148, v148, v149
	v_add_f32_e32 v146, v146, v148
	v_exp_f32_e32 v84, v84
	v_exp_f32_e32 v85, v85
	v_exp_f32_e32 v86, v86
	v_exp_f32_e32 v87, v87
	v_exp_f32_e32 v88, v88
	v_exp_f32_e32 v89, v89
	v_exp_f32_e32 v90, v90
	v_exp_f32_e32 v91, v91
	v_exp_f32_e32 v92, v92
	v_exp_f32_e32 v93, v93
	v_exp_f32_e32 v94, v94
	v_exp_f32_e32 v95, v95
	v_exp_f32_e32 v164, v164
	v_exp_f32_e32 v165, v165
	v_exp_f32_e32 v166, v166
	v_exp_f32_e32 v167, v167
	v_add_f32_e32 v148, v84, v85
	v_add_f32_e32 v149, v86, v87
	v_add_f32_e32 v150, v88, v89
	v_add_f32_e32 v151, v90, v91
	v_add_f32_e32 v152, v92, v93
	v_add_f32_e32 v153, v94, v95
	v_add_f32_e32 v154, v164, v165
	v_add_f32_e32 v155, v166, v167
	v_add_f32_e32 v148, v148, v149
	v_add_f32_e32 v149, v150, v151
	v_add_f32_e32 v150, v152, v153
	v_add_f32_e32 v151, v154, v155
	v_add_f32_e32 v148, v148, v149
	v_add_f32_e32 v150, v150, v151
	v_add_f32_e32 v148, v148, v150
	v_max_f32_e32 v147, v146, v148
	v_cmp_lt_f32_e32 vcc, 0x69800000, v147
	s_cbranch_vccnz .Lfox1_dfallback
	v_add_f32_e32 v128, v128, v146
	v_add_f32_e32 v129, v129, v148
	v_cvt_pk_bf16_f32 v36, v72, v73
	v_cvt_pk_bf16_f32 v37, v74, v75
	v_cvt_pk_bf16_f32 v38, v76, v77
	v_cvt_pk_bf16_f32 v39, v78, v79
	v_cvt_pk_bf16_f32 v28, v80, v81
	v_cvt_pk_bf16_f32 v29, v82, v83
	v_cvt_pk_bf16_f32 v30, v96, v97
	v_cvt_pk_bf16_f32 v31, v98, v99
	s_cmp_eq_u32 s99, 0
	s_cbranch_scc1 .Lfox1_nm4
	s_barrier

; DI f32x4 mmaT(bf16x8 a_m, bf16x8 b_n, f32x4 c) { return __builtin_amdgcn_mfma_f32_16x16x32_bf16(b_n, a_m, c, 0, 0, 0); }
; DI v4i16_t tr_rd(const bf16_t* a) { return __builtin_amdgcn_ds_read_tr16_b64_v4i16((LDSP v4i16_t*)a); }
; template <bool DIAG>
; DI void fox_tile(const bf16_t* sK, const bf16_t* sV, const float* sFk, const bf16x8 (&qf)[2][2], f32x4 (&o)[2][4], float (&mrun)[2], float (&lsum)[2], int key0, int qg0, int fr, int fq, int lane) {
;   const float SC2 = 0.125f * LOG2E;
;   f32x4 s[2][4];
;   const int kof = (fr * 64 + fq * 16) ^ ((fr >> 3) << 5);
; #pragma unroll
;   for (int t = 0; t < 4; ++t) {
;     const bf16x8 k0 = *(const bf16x8*)((const unsigned char*)sK + (t * 2) * 1024 + kof), k1 = *(const bf16x8*)((const unsigned char*)sK + (t * 2 + 1) * 1024 + kof);
; #pragma unroll
;     for (int mi = 0; mi < 2; ++mi) { s[mi][t] = mmaT(qf[mi][0], k0, (f32x4){0.f, 0.f, 0.f, 0.f}); s[mi][t] = mmaT(qf[mi][1], k1, s[mi][t]); }
;   }
;   f32x4 fk[4];
; #pragma unroll
;   for (int t = 0; t < 4; ++t) fk[t] = *(const f32x4*)(sFk + 16 * t + 4 * fq);
;   __builtin_amdgcn_sched_barrier(0);
;   bf16x8 vf[2][4];
; #pragma unroll
;   for (int k2 = 0; k2 < 2; ++k2)
; #pragma unroll
;     for (int d = 0; d < 4; ++d) {
;       const bf16_t* a = sV + (32 * k2 + 4 * fq + (fr >> 2)) * 72 + 16 * d + 4 * (fr & 3);
;       const v4i16_t lo = tr_rd(a), hi = tr_rd(a + 16 * 72);
;       vf[k2][d] = __builtin_shufflevector(lo, hi, 0, 1, 2, 3, 4, 5, 6, 7);
;     }
;   __builtin_amdgcn_sched_barrier(0);
.Lfox1_dslow:
	s_waitcnt lgkmcnt(11)
	v_mfma_f32_16x16x32_bf16 v[72:75], v[64:67], v[0:3], 0
	s_waitcnt lgkmcnt(10)
	v_mfma_f32_16x16x32_bf16 v[146:149], v[68:71], v[4:7], v[72:75]
	v_mfma_f32_16x16x32_bf16 v[72:75], v[64:67], v[8:11], 0
	v_mfma_f32_16x16x32_bf16 v[164:167], v[68:71], v[12:15], v[72:75]
	s_waitcnt lgkmcnt(9)
	v_mfma_f32_16x16x32_bf16 v[72:75], v[56:59], v[0:3], 0
	s_waitcnt lgkmcnt(8)
	v_mfma_f32_16x16x32_bf16 v[150:153], v[60:63], v[4:7], v[72:75]
	v_mfma_f32_16x16x32_bf16 v[72:75], v[56:59], v[8:11], 0
	v_mfma_f32_16x16x32_bf16 v[222:225], v[60:63], v[12:15], v[72:75]
	s_waitcnt lgkmcnt(7)
	v_mfma_f32_16x16x32_bf16 v[72:75], v[48:51], v[0:3], 0
	s_waitcnt lgkmcnt(6)
	v_mfma_f32_16x16x32_bf16 v[154:157], v[52:55], v[4:7], v[72:75]
	v_mfma_f32_16x16x32_bf16 v[72:75], v[48:51], v[8:11], 0
	v_mfma_f32_16x16x32_bf16 v[226:229], v[52:55], v[12:15], v[72:75]
	s_waitcnt lgkmcnt(5)
	v_mfma_f32_16x16x32_bf16 v[72:75], v[40:43], v[0:3], 0
	s_waitcnt lgkmcnt(4)
	v_mfma_f32_16x16x32_bf16 v[172:175], v[44:47], v[4:7], v[72:75]
	v_mfma_f32_16x16x32_bf16 v[72:75], v[40:43], v[8:11], 0
	v_mfma_f32_16x16x32_bf16 v[104:107], v[44:47], v[12:15], v[72:75]
	ds_read_b64_tr_b16 v[100:101], v221 offset:9216
	ds_read_b64_tr_b16 v[92:93], v221 offset:9248
	ds_read_b64_tr_b16 v[96:97], v221 offset:9280
	ds_read_b64_tr_b16 v[88:89], v221 offset:9312
	ds_read_b64_tr_b16 v[102:103], v221 offset:11520
	ds_read_b64_tr_b16 v[94:95], v221 offset:11552
	ds_read_b64_tr_b16 v[98:99], v221 offset:11584
	ds_read_b64_tr_b16 v[90:91], v221 offset:11616
	ds_read_b64_tr_b16 v[84:85], v221 offset:13824
	ds_read_b64_tr_b16 v[80:81], v221 offset:13856
	ds_read_b64_tr_b16 v[76:77], v221 offset:13888
	ds_read_b64_tr_b16 v[72:73], v221 offset:13920
	ds_read_b64_tr_b16 v[86:87], v221 offset:16128
	ds_read_b64_tr_b16 v[82:83], v221 offset:16160
	ds_read_b64_tr_b16 v[78:79], v221 offset:16192
	ds_read_b64_tr_b16 v[74:75], v221 offset:16224
	s_cmp_eq_u32 s99, 0
	s_cbranch_scc1 .Lfox1_nm1
	s_barrier

; DI float ex2(float x) { return __builtin_amdgcn_exp2f(x); }
; DI f32x4 mmaT(bf16x8 a_m, bf16x8 b_n, f32x4 c) { return __builtin_amdgcn_mfma_f32_16x16x32_bf16(b_n, a_m, c, 0, 0, 0); }
; template <bool DIAG>
; DI void fox_tile(const bf16_t* sK, const bf16_t* sV, const float* sFk, const bf16x8 (&qf)[2][2], f32x4 (&o)[2][4], float (&mrun)[2], float (&lsum)[2], int key0, int qg0, int fr, int fq, int lane) {
;   const float SC2 = 0.125f * LOG2E;
;   f32x4 s[2][4];
;   const int kof = (fr * 64 + fq * 16) ^ ((fr >> 3) << 5);
; #pragma unroll
;   for (int t = 0; t < 4; ++t) {
;     const bf16x8 k0 = *(const bf16x8*)((const unsigned char*)sK + (t * 2) * 1024 + kof), k1 = *(const bf16x8*)((const unsigned char*)sK + (t * 2 + 1) * 1024 + kof);
; #pragma unroll
;     for (int mi = 0; mi < 2; ++mi) { s[mi][t] = mmaT(qf[mi][0], k0, (f32x4){0.f, 0.f, 0.f, 0.f}); s[mi][t] = mmaT(qf[mi][1], k1, s[mi][t]); }
;   }
;   f32x4 fk[4];
; #pragma unroll
;   for (int t = 0; t < 4; ++t) fk[t] = *(const f32x4*)(sFk + 16 * t + 4 * fq);
;   __builtin_amdgcn_sched_barrier(0);
;   bf16x8 vf[2][4];
; #pragma unroll
;   for (int k2 = 0; k2 < 2; ++k2)
; #pragma unroll
;     for (int d = 0; d < 4; ++d) {
;       const bf16_t* a = sV + (32 * k2 + 4 * fq + (fr >> 2)) * 72 + 16 * d + 4 * (fr & 3);
;       const v4i16_t lo = tr_rd(a), hi = tr_rd(a + 16 * 72);
;       vf[k2][d] = __builtin_shufflevector(lo, hi, 0, 1, 2, 3, 4, 5, 6, 7);
;     }
;   __builtin_amdgcn_sched_barrier(0);
; #pragma unroll
;   for (int mi = 0; mi < 2; ++mi) {
;     float mx = -INFINITY;
; #pragma unroll
;     for (int t = 0; t < 4; ++t)
; #pragma unroll
;       for (int j = 0; j < 4; ++j) {
;         float x = __builtin_fmaf(s[mi][t][j], SC2, fk[t][j]);
;         if (DIAG) { if (key0 + 16 * t + 4 * fq + j > qg0 + 16 * mi) x = -INFINITY; }
;         s[mi][t][j] = x; mx = fmaxf(mx, x);
;       }
;     mx = fmaxf(mx, shx(mx, 16, lane)); mx = fmaxf(mx, shx(mx, 32, lane));
;     const float mnew = fmaxf(mrun[mi], mx), alpha = ex2(mrun[mi] - mnew);
;     mrun[mi] = mnew;
;     float ps = 0.f;
; #pragma unroll
;     for (int t = 0; t < 4; ++t)
; #pragma unroll
;       for (int j = 0; j < 4; ++j) { const float pv = ex2(s[mi][t][j] - mnew); s[mi][t][j] = pv; ps += pv; }
;     lsum[mi] = lsum[mi] * alpha + ps;
; #pragma unroll
;     for (int d = 0; d < 4; ++d) o[mi][d] *= alpha;
;   }
.LBB0_609:
	s_mul_i32 s4, s20, 0x4900
	s_add_i32 s4, s4, 32
	v_add_u32_e32 v24, s4, v213
	ds_read_b128 v[64:67], v24
	ds_read_b128 v[68:71], v24 offset:1024
	ds_read_b128 v[56:59], v24 offset:2048
	ds_read_b128 v[60:63], v24 offset:3072
	ds_read_b128 v[48:51], v24 offset:4096
	ds_read_b128 v[52:55], v24 offset:5120
	ds_read_b128 v[40:43], v24 offset:6144
	ds_read_b128 v[44:47], v24 offset:7168
	v_lshl_add_u32 v24, v209, 2, s4
	ds_read_b128 v[36:39], v24 offset:18432
	ds_read_b128 v[32:35], v24 offset:18496
	ds_read_b128 v[28:31], v24 offset:18560
	ds_read_b128 v[24:27], v24 offset:18624
	v_lshl_add_u32 v72, v214, 1, s4
	v_readfirstlane_b32 s100, v212
	s_add_i32 s101, s17, 94
	s_mov_b64 s[4:5], -1
	v_add_u32_e32 v221, v72, v215
	s_cmp_le_i32 s101, s100
	s_cbranch_scc1 .LBB0_611
	s_waitcnt lgkmcnt(11)
	v_mfma_f32_16x16x32_bf16 v[72:75], v[64:67], v[0:3], v[224:227]
	s_waitcnt lgkmcnt(10)
	v_mfma_f32_16x16x32_bf16 v[72:75], v[68:71], v[4:7], v[72:75]
	s_waitcnt lgkmcnt(9)
	v_mfma_f32_16x16x32_bf16 v[76:79], v[56:59], v[0:3], v[224:227]
	s_waitcnt lgkmcnt(8)
	v_mfma_f32_16x16x32_bf16 v[76:79], v[60:63], v[4:7], v[76:79]
	s_waitcnt lgkmcnt(7)
	v_mfma_f32_16x16x32_bf16 v[80:83], v[48:51], v[0:3], v[224:227]
	s_waitcnt lgkmcnt(6)
	v_mfma_f32_16x16x32_bf16 v[80:83], v[52:55], v[4:7], v[80:83]
	s_waitcnt lgkmcnt(5)
	v_mfma_f32_16x16x32_bf16 v[96:99], v[40:43], v[0:3], v[224:227]
	s_waitcnt lgkmcnt(4)
	v_mfma_f32_16x16x32_bf16 v[96:99], v[44:47], v[4:7], v[96:99]
	s_waitcnt lgkmcnt(0)
	v_add_u32_e32 v172, s17, v209
	v_sub_u32_e32 v172, v172, v206
	v_add_u32_e32 v176, -16, v172
	v_add_u32_e32 v173, 16, v172
	v_add_u32_e32 v177, 16, v176
	v_add_u32_e32 v174, 32, v172
	v_add_u32_e32 v178, 32, v176
	v_add_u32_e32 v175, 48, v172
	v_add_u32_e32 v179, 48, v176
	v_mfma_f32_16x16x32_bf16 v[84:87], v[64:67], v[8:11], v[228:231]
	v_mfma_f32_16x16x32_bf16 v[84:87], v[68:71], v[12:15], v[84:87]
	v_fmamk_f32 v72, v72, 0x3e38aa3b, v36
	v_fmamk_f32 v73, v73, 0x3e38aa3b, v37
	v_fmamk_f32 v74, v74, 0x3e38aa3b, v38
	v_fmamk_f32 v75, v75, 0x3e38aa3b, v39
	v_mfma_f32_16x16x32_bf16 v[88:91], v[56:59], v[8:11], v[228:231]
	v_mfma_f32_16x16x32_bf16 v[88:91], v[60:63], v[12:15], v[88:91]
	v_fmamk_f32 v76, v76, 0x3e38aa3b, v32
	v_fmamk_f32 v77, v77, 0x3e38aa3b, v33
	v_fmamk_f32 v78, v78, 0x3e38aa3b, v34
	v_fmamk_f32 v79, v79, 0x3e38aa3b, v35
	v_mfma_f32_16x16x32_bf16 v[92:95], v[48:51], v[8:11], v[228:231]
	v_mfma_f32_16x16x32_bf16 v[92:95], v[52:55], v[12:15], v[92:95]
	v_fmamk_f32 v80, v80, 0x3e38aa3b, v28
	v_fmamk_f32 v81, v81, 0x3e38aa3b, v29
	v_fmamk_f32 v82, v82, 0x3e38aa3b, v30
	v_fmamk_f32 v83, v83, 0x3e38aa3b, v31
	v_mfma_f32_16x16x32_bf16 v[164:167], v[40:43], v[8:11], v[228:231]
	v_mfma_f32_16x16x32_bf16 v[164:167], v[44:47], v[12:15], v[164:167]
	v_fmamk_f32 v96, v96, 0x3e38aa3b, v24
	v_fmamk_f32 v97, v97, 0x3e38aa3b, v25
	v_fmamk_f32 v98, v98, 0x3e38aa3b, v26
	v_fmamk_f32 v99, v99, 0x3e38aa3b, v27
	ds_read_b64_tr_b16 v[68:69], v221 offset:9216
	ds_read_b64_tr_b16 v[60:61], v221 offset:9248
	ds_read_b64_tr_b16 v[64:65], v221 offset:9280
	ds_read_b64_tr_b16 v[56:57], v221 offset:9312
	ds_read_b64_tr_b16 v[70:71], v221 offset:11520
	ds_read_b64_tr_b16 v[62:63], v221 offset:11552
	ds_read_b64_tr_b16 v[66:67], v221 offset:11584
	ds_read_b64_tr_b16 v[58:59], v221 offset:11616
	ds_read_b64_tr_b16 v[52:53], v221 offset:13824
	ds_read_b64_tr_b16 v[48:49], v221 offset:13856
	ds_read_b64_tr_b16 v[44:45], v221 offset:13888
	ds_read_b64_tr_b16 v[40:41], v221 offset:13920
	ds_read_b64_tr_b16 v[54:55], v221 offset:16128
	ds_read_b64_tr_b16 v[50:51], v221 offset:16160
	ds_read_b64_tr_b16 v[46:47], v221 offset:16192
	ds_read_b64_tr_b16 v[42:43], v221 offset:16224
	v_cmp_ge_i32_e32 vcc, 0, v172
	v_cmp_ge_i32_e64 s[4:5], -1, v172
	v_cmp_ge_i32_e64 s[100:101], -2, v172
	v_cndmask_b32_e32 v72, v200, v72, vcc
	v_cndmask_b32_e64 v73, v200, v73, s[4:5]
	v_cndmask_b32_e64 v74, v200, v74, s[100:101]
	v_cmp_ge_i32_e32 vcc, -3, v172
	v_cmp_ge_i32_e64 s[4:5], 0, v173
	v_cmp_ge_i32_e64 s[100:101], -1, v173
	v_cndmask_b32_e32 v75, v200, v75, vcc
	v_cndmask_b32_e64 v76, v200, v76, s[4:5]
	v_cndmask_b32_e64 v77, v200, v77, s[100:101]
	v_cmp_ge_i32_e32 vcc, -2, v173
	v_cmp_ge_i32_e64 s[4:5], -3, v173
	v_cmp_ge_i32_e64 s[100:101], 0, v174
	v_cndmask_b32_e32 v78, v200, v78, vcc
	v_cndmask_b32_e64 v79, v200, v79, s[4:5]
	v_cndmask_b32_e64 v80, v200, v80, s[100:101]
	v_cmp_ge_i32_e32 vcc, -1, v174
	v_cmp_ge_i32_e64 s[4:5], -2, v174
	v_cmp_ge_i32_e64 s[100:101], -3, v174
; DI unsigned pk2(float lo, float hi) { unsigned r; asm volatile("v_cvt_pk_bf16_f32 %0, %1, %2" : "=v"(r) : "v"(lo), "v"(hi)); return r; }
; DI float ex2(float x) { return __builtin_amdgcn_exp2f(x); }
; DI float shx(float v, int m, int lane) { return __int_as_float(__builtin_amdgcn_ds_bpermute((lane ^ m) << 2, __float_as_int(v))); }
; template <bool DIAG>
; DI void fox_tile(const bf16_t* sK, const bf16_t* sV, const float* sFk, const bf16x8 (&qf)[2][2], f32x4 (&o)[2][4], float (&mrun)[2], float (&lsum)[2], int key0, int qg0, int fr, int fq, int lane) {
;     ...
;   for (int mi = 0; mi < 2; ++mi) {
;     float mx = -INFINITY;
; #pragma unroll
;     for (int t = 0; t < 4; ++t)
; #pragma unroll
;       for (int j = 0; j < 4; ++j) {
;         float x = __builtin_fmaf(s[mi][t][j], SC2, fk[t][j]);
;         if (DIAG) { if (key0 + 16 * t + 4 * fq + j > qg0 + 16 * mi) x = -INFINITY; }
;         s[mi][t][j] = x; mx = fmaxf(mx, x);
;       }
;     mx = fmaxf(mx, shx(mx, 16, lane)); mx = fmaxf(mx, shx(mx, 32, lane));
;     const float mnew = fmaxf(mrun[mi], mx), alpha = ex2(mrun[mi] - mnew);
;     mrun[mi] = mnew;
;     float ps = 0.f;
; #pragma unroll
;     for (int t = 0; t < 4; ++t)
; #pragma unroll
;       for (int j = 0; j < 4; ++j) { const float pv = ex2(s[mi][t][j] - mnew); s[mi][t][j] = pv; ps += pv; }
;     lsum[mi] = lsum[mi] * alpha + ps;
; #pragma unroll
;     for (int d = 0; d < 4; ++d) o[mi][d] *= alpha;
;   }
; #pragma unroll
;   for (int k2 = 0; k2 < 2; ++k2) {
;     bf16x8 pa[2];
; #pragma unroll
;     for (int mi = 0; mi < 2; ++mi) pa[mi] = mk8(pk2(s[mi][2 * k2][0], s[mi][2 * k2][1]), pk2(s[mi][2 * k2][2], s[mi][2 * k2][3]), pk2(s[mi][2 * k2 + 1][0], s[mi][2 * k2 + 1][1]), pk2(s[mi][2 * k2 + 1][2], s[mi][2 * k2 + 1][3]));
	v_cndmask_b32_e32 v81, v200, v81, vcc
	v_cndmask_b32_e64 v82, v200, v82, s[4:5]
	v_cndmask_b32_e64 v83, v200, v83, s[100:101]
	v_cmp_ge_i32_e32 vcc, 0, v175
	v_cmp_ge_i32_e64 s[4:5], -1, v175
	v_cmp_ge_i32_e64 s[100:101], -2, v175
	v_cndmask_b32_e32 v96, v200, v96, vcc
	v_cndmask_b32_e64 v97, v200, v97, s[4:5]
	v_cndmask_b32_e64 v98, v200, v98, s[100:101]
	v_cmp_ge_i32_e32 vcc, -3, v175
	s_nop 1
	v_cndmask_b32_e32 v99, v200, v99, vcc
	v_exp_f32_e32 v72, v72
	v_exp_f32_e32 v73, v73
	v_exp_f32_e32 v74, v74
	v_exp_f32_e32 v75, v75
	v_exp_f32_e32 v76, v76
	v_exp_f32_e32 v77, v77
	v_exp_f32_e32 v78, v78
	v_exp_f32_e32 v79, v79
	v_exp_f32_e32 v80, v80
	v_exp_f32_e32 v81, v81
	v_exp_f32_e32 v82, v82
	v_exp_f32_e32 v83, v83
	v_exp_f32_e32 v96, v96
	v_exp_f32_e32 v97, v97
	v_exp_f32_e32 v98, v98
	v_exp_f32_e32 v99, v99
	v_fmamk_f32 v84, v84, 0x3e38aa3b, v36
	v_fmamk_f32 v85, v85, 0x3e38aa3b, v37
	v_fmamk_f32 v86, v86, 0x3e38aa3b, v38
	v_fmamk_f32 v87, v87, 0x3e38aa3b, v39
	v_fmamk_f32 v88, v88, 0x3e38aa3b, v32
	v_fmamk_f32 v89, v89, 0x3e38aa3b, v33
	v_fmamk_f32 v90, v90, 0x3e38aa3b, v34
	v_fmamk_f32 v91, v91, 0x3e38aa3b, v35
	v_fmamk_f32 v92, v92, 0x3e38aa3b, v28
	v_fmamk_f32 v93, v93, 0x3e38aa3b, v29
	v_fmamk_f32 v94, v94, 0x3e38aa3b, v30
	v_fmamk_f32 v95, v95, 0x3e38aa3b, v31
	v_fmamk_f32 v164, v164, 0x3e38aa3b, v24
	v_fmamk_f32 v165, v165, 0x3e38aa3b, v25
	v_fmamk_f32 v166, v166, 0x3e38aa3b, v26
	v_fmamk_f32 v167, v167, 0x3e38aa3b, v27
	v_cmp_ge_i32_e32 vcc, 0, v176
	v_cmp_ge_i32_e64 s[4:5], -1, v176
	v_cmp_ge_i32_e64 s[100:101], -2, v176
	v_cndmask_b32_e32 v84, v200, v84, vcc
	v_cndmask_b32_e64 v85, v200, v85, s[4:5]
	v_cndmask_b32_e64 v86, v200, v86, s[100:101]
	v_cmp_ge_i32_e32 vcc, -3, v176
	v_cmp_ge_i32_e64 s[4:5], 0, v177
	v_cmp_ge_i32_e64 s[100:101], -1, v177
	v_cndmask_b32_e32 v87, v200, v87, vcc
	v_cndmask_b32_e64 v88, v200, v88, s[4:5]
	v_cndmask_b32_e64 v89, v200, v89, s[100:101]
	v_cmp_ge_i32_e32 vcc, -2, v177
	v_cmp_ge_i32_e64 s[4:5], -3, v177
	v_cmp_ge_i32_e64 s[100:101], 0, v178
	v_cndmask_b32_e32 v90, v200, v90, vcc
	v_cndmask_b32_e64 v91, v200, v91, s[4:5]
	v_cndmask_b32_e64 v92, v200, v92, s[100:101]
	v_cmp_ge_i32_e32 vcc, -1, v178
	v_cmp_ge_i32_e64 s[4:5], -2, v178
	v_cmp_ge_i32_e64 s[100:101], -3, v178
	v_cndmask_b32_e32 v93, v200, v93, vcc
	v_cndmask_b32_e64 v94, v200, v94, s[4:5]
	v_cndmask_b32_e64 v95, v200, v95, s[100:101]
	v_cmp_ge_i32_e32 vcc, 0, v179
	v_cmp_ge_i32_e64 s[4:5], -1, v179
	v_cmp_ge_i32_e64 s[100:101], -2, v179
	v_cndmask_b32_e32 v164, v200, v164, vcc
	v_cndmask_b32_e64 v165, v200, v165, s[4:5]
	v_cndmask_b32_e64 v166, v200, v166, s[100:101]
	v_cmp_ge_i32_e32 vcc, -3, v179
	s_nop 1
	v_cndmask_b32_e32 v167, v200, v167, vcc
	v_add_f32_e32 v146, v72, v73
	v_add_f32_e32 v147, v74, v75
	v_add_f32_e32 v148, v76, v77
	v_add_f32_e32 v149, v78, v79
	v_add_f32_e32 v150, v80, v81
	v_add_f32_e32 v151, v82, v83
	v_add_f32_e32 v152, v96, v97
	v_add_f32_e32 v153, v98, v99
	v_add_f32_e32 v146, v146, v147
	v_add_f32_e32 v147, v148, v149
	v_add_f32_e32 v148, v150, v151
	v_add_f32_e32 v149, v152, v153
	v_add_f32_e32 v146, v146, v147
	v_add_f32_e32 v148, v148, v149
	v_add_f32_e32 v146, v146, v148
	v_exp_f32_e32 v84, v84
	v_exp_f32_e32 v85, v85
	v_exp_f32_e32 v86, v86
	v_exp_f32_e32 v87, v87
	v_exp_f32_e32 v88, v88
	v_exp_f32_e32 v89, v89
	v_exp_f32_e32 v90, v90
	v_exp_f32_e32 v91, v91
	v_exp_f32_e32 v92, v92
	v_exp_f32_e32 v93, v93
	v_exp_f32_e32 v94, v94
	v_exp_f32_e32 v95, v95
	v_exp_f32_e32 v164, v164
	v_exp_f32_e32 v165, v165
	v_exp_f32_e32 v166, v166
	v_exp_f32_e32 v167, v167
	v_add_f32_e32 v148, v84, v85
	v_add_f32_e32 v149, v86, v87
	v_add_f32_e32 v150, v88, v89
	v_add_f32_e32 v151, v90, v91
	v_add_f32_e32 v152, v92, v93
	v_add_f32_e32 v153, v94, v95
	v_add_f32_e32 v154, v164, v165
	v_add_f32_e32 v155, v166, v167
	v_add_f32_e32 v148, v148, v149
	v_add_f32_e32 v149, v150, v151
	v_add_f32_e32 v150, v152, v153
	v_add_f32_e32 v151, v154, v155
	v_add_f32_e32 v148, v148, v149
	v_add_f32_e32 v150, v150, v151
	v_add_f32_e32 v148, v148, v150
	v_max_f32_e32 v147, v146, v148
	v_cmp_lt_f32_e32 vcc, 0x69800000, v147
	s_cbranch_vccnz .Lfox2_dfallback
	v_add_f32_e32 v128, v128, v146
	v_add_f32_e32 v129, v129, v148
	v_cvt_pk_bf16_f32 v36, v72, v73
	v_cvt_pk_bf16_f32 v37, v74, v75
	v_cvt_pk_bf16_f32 v38, v76, v77
	v_cvt_pk_bf16_f32 v39, v78, v79
	v_cvt_pk_bf16_f32 v28, v80, v81
	v_cvt_pk_bf16_f32 v29, v82, v83
	v_cvt_pk_bf16_f32 v30, v96, v97
	v_cvt_pk_bf16_f32 v31, v98, v99
	s_cmp_eq_u32 s99, 0
	s_cbranch_scc1 .Lfox2_nm4
	s_barrier

; DI f32x4 mmaT(bf16x8 a_m, bf16x8 b_n, f32x4 c) { return __builtin_amdgcn_mfma_f32_16x16x32_bf16(b_n, a_m, c, 0, 0, 0); }
; DI v4i16_t tr_rd(const bf16_t* a) { return __builtin_amdgcn_ds_read_tr16_b64_v4i16((LDSP v4i16_t*)a); }
; template <bool DIAG>
; DI void fox_tile(const bf16_t* sK, const bf16_t* sV, const float* sFk, const bf16x8 (&qf)[2][2], f32x4 (&o)[2][4], float (&mrun)[2], float (&lsum)[2], int key0, int qg0, int fr, int fq, int lane) {
;   const float SC2 = 0.125f * LOG2E;
;   f32x4 s[2][4];
;   const int kof = (fr * 64 + fq * 16) ^ ((fr >> 3) << 5);
; #pragma unroll
;   for (int t = 0; t < 4; ++t) {
;     const bf16x8 k0 = *(const bf16x8*)((const unsigned char*)sK + (t * 2) * 1024 + kof), k1 = *(const bf16x8*)((const unsigned char*)sK + (t * 2 + 1) * 1024 + kof);
; #pragma unroll
;     for (int mi = 0; mi < 2; ++mi) { s[mi][t] = mmaT(qf[mi][0], k0, (f32x4){0.f, 0.f, 0.f, 0.f}); s[mi][t] = mmaT(qf[mi][1], k1, s[mi][t]); }
;   }
;   f32x4 fk[4];
; #pragma unroll
;   for (int t = 0; t < 4; ++t) fk[t] = *(const f32x4*)(sFk + 16 * t + 4 * fq);
;   __builtin_amdgcn_sched_barrier(0);
;   bf16x8 vf[2][4];
; #pragma unroll
;   for (int k2 = 0; k2 < 2; ++k2)
; #pragma unroll
;     for (int d = 0; d < 4; ++d) {
;       const bf16_t* a = sV + (32 * k2 + 4 * fq + (fr >> 2)) * 72 + 16 * d + 4 * (fr & 3);
;       const v4i16_t lo = tr_rd(a), hi = tr_rd(a + 16 * 72);
;       vf[k2][d] = __builtin_shufflevector(lo, hi, 0, 1, 2, 3, 4, 5, 6, 7);
;     }
;   __builtin_amdgcn_sched_barrier(0);
.Lfox2_dslow:
	s_waitcnt lgkmcnt(11)
	v_mfma_f32_16x16x32_bf16 v[72:75], v[64:67], v[0:3], 0
	s_waitcnt lgkmcnt(10)
	v_mfma_f32_16x16x32_bf16 v[146:149], v[68:71], v[4:7], v[72:75]
	v_mfma_f32_16x16x32_bf16 v[72:75], v[64:67], v[8:11], 0
	v_mfma_f32_16x16x32_bf16 v[222:225], v[68:71], v[12:15], v[72:75]
	s_waitcnt lgkmcnt(9)
	v_mfma_f32_16x16x32_bf16 v[72:75], v[56:59], v[0:3], 0
	s_waitcnt lgkmcnt(8)
	v_mfma_f32_16x16x32_bf16 v[150:153], v[60:63], v[4:7], v[72:75]
	v_mfma_f32_16x16x32_bf16 v[72:75], v[56:59], v[8:11], 0
	v_mfma_f32_16x16x32_bf16 v[226:229], v[60:63], v[12:15], v[72:75]
	s_waitcnt lgkmcnt(7)
	v_mfma_f32_16x16x32_bf16 v[72:75], v[48:51], v[0:3], 0
	s_waitcnt lgkmcnt(6)
	v_mfma_f32_16x16x32_bf16 v[154:157], v[52:55], v[4:7], v[72:75]
	v_mfma_f32_16x16x32_bf16 v[72:75], v[48:51], v[8:11], 0
	v_mfma_f32_16x16x32_bf16 v[230:233], v[52:55], v[12:15], v[72:75]
	s_waitcnt lgkmcnt(5)
	v_mfma_f32_16x16x32_bf16 v[72:75], v[40:43], v[0:3], 0
	s_waitcnt lgkmcnt(4)
	v_mfma_f32_16x16x32_bf16 v[172:175], v[44:47], v[4:7], v[72:75]
	v_mfma_f32_16x16x32_bf16 v[72:75], v[40:43], v[8:11], 0
	v_mfma_f32_16x16x32_bf16 v[104:107], v[44:47], v[12:15], v[72:75]
	ds_read_b64_tr_b16 v[100:101], v221 offset:9216
	ds_read_b64_tr_b16 v[92:93], v221 offset:9248
	ds_read_b64_tr_b16 v[96:97], v221 offset:9280
	ds_read_b64_tr_b16 v[88:89], v221 offset:9312
	ds_read_b64_tr_b16 v[102:103], v221 offset:11520
	ds_read_b64_tr_b16 v[94:95], v221 offset:11552
	ds_read_b64_tr_b16 v[98:99], v221 offset:11584
	ds_read_b64_tr_b16 v[90:91], v221 offset:11616
	ds_read_b64_tr_b16 v[84:85], v221 offset:13824
	ds_read_b64_tr_b16 v[80:81], v221 offset:13856
	ds_read_b64_tr_b16 v[76:77], v221 offset:13888
	ds_read_b64_tr_b16 v[72:73], v221 offset:13920
	ds_read_b64_tr_b16 v[86:87], v221 offset:16128
	ds_read_b64_tr_b16 v[82:83], v221 offset:16160
	ds_read_b64_tr_b16 v[78:79], v221 offset:16192
	ds_read_b64_tr_b16 v[74:75], v221 offset:16224
	s_cmp_eq_u32 s99, 0
	s_cbranch_scc1 .Lfox2_nm1
	s_barrier
